# pooling mixer rewritten by hand: tree window sums + f32 MFMA (32x32x2) matmul, one barrier less per tile
# speedup vs baseline: 1.0517x; 1.0517x over previous
; DI float bf2f(u16 v) { return __uint_as_float(((unsigned)v) << 16); }
; DI void pool_item(const Params& P, unsigned char* lds, const int l, const int tt, const int tid) {
;     ...
;       u16* U = (u16*)lds;
;       float* Y = (float*)(lds + 80 * 256 * 2);
;       int s0, n;
;       if (lat) { s0 = (row0 >> 11) << 11; n = 2048; } else { s0 = M_LAT + (((row0 - M_LAT) >> 8) << 8); n = 256; }
;       const int t0 = row0 - s0;
;       for (int idx = tid; idx < 80 * 32; idx += 512) {
;         int rr = idx >> 5, c8 = idx & 31;
;         int t = t0 - 8 + rr;
;         u32x4 v = (u32x4){0u, 0u, 0u, 0u};
;         if (t >= 0 && t < n) v = *(const u32x4*)(p + (size_t)(s0 + t) * DIN + 768 + c8 * 8);
;         *(u32x4*)(U + rr * 256 + c8 * 8) = v;
;       }
;       __syncthreads();
;       {
;         const int ch = tid & 255, tg = tid >> 8, g = ch >> 6, w = 2 << g;
;         for (int tk = 0; tk < 32; ++tk) {
;           int tok = tg * 32 + tk, t = t0 + tok;
;           int lo = max(t - (w >> 1), 0), hi = min(t - (w >> 1) + w, n);
;           float s = 0.f;
;           for (int q = lo; q < hi; ++q) s += bf2f(U[(q - t0 + 8) * 256 + ch]);
;           float mean = s / (float)(hi - lo);
;           Y[tok * 256 + ch] = mean - bf2f(U[(tok + 8) * 256 + ch]);
;         }
;       }
;       __syncthreads();
;       {
;         const int dcol = tid & 255, tg = tid >> 8, g = dcol >> 6, d = dcol & 63;
;         const float* pw = P.pool_w + ((size_t)(l * 4 + g) * 64) * 64 + d;
;         float acc[32];
; #pragma unroll
;         for (int tk = 0; tk < 32; ++tk) acc[tk] = 0.f;
;         for (int c4 = 0; c4 < 16; ++c4) {
;           float w0 = pw[(c4 * 4 + 0) * 64], w1 = pw[(c4 * 4 + 1) * 64], w2 = pw[(c4 * 4 + 2) * 64], w3 = pw[(c4 * 4 + 3) * 64];
.LBB0_484:
	s_lshl_b32 s14, s9, 6
	s_cmpk_lt_i32 s9, 0x100
	s_movk_i32 s2, 0x800
	s_cselect_b32 s15, s2, 0x100
	s_movk_i32 s2, 0xf800
	s_cselect_b32 s2, s2, 0x7fffff00
	s_and_b32 s16, s2, s14
	s_sub_i32 s17, s14, s16
	v_mbcnt_lo_u32_b32 v6, -1, 0
	v_mbcnt_hi_u32_b32 v6, -1, v6
	v_or_b32_e32 v6, s90, v6
	s_lshr_b32 s2, s90, 6
	s_and_b32 s3, s2, 3
	s_lshr_b32 s4, s2, 2
	v_readlane_b32 s20, v253, 59
	v_readlane_b32 s21, v253, 60
	s_add_i32 s5, s22, s3
	s_lshl_b32 s5, s5, 14
	s_add_u32 s20, s20, s5
	s_addc_u32 s21, s21, 0
	s_sub_u32 s20, s20, 0x200
	s_subb_u32 s21, s21, 0
	s_add_u32 s38, s20, 0x1000
	s_addc_u32 s39, s21, 0
	s_add_u32 s40, s20, 0x2000
	s_addc_u32 s41, s21, 0
	s_add_u32 s42, s20, 0x3000
	s_addc_u32 s43, s21, 0
	v_and_b32_e32 v7, 31, v6
	v_bfe_u32 v8, v6, 5, 1
	v_lshlrev_b32_e32 v9, 8, v8
	v_lshl_add_u32 v9, v7, 2, v9
	v_lshrrev_b32_e32 v10, 5, v6
	v_mul_u32_u24_e32 v11, 0xe00, v10
	v_lshl_add_u32 v11, v7, 4, v11
	v_readlane_b32 s6, v254, 45
	v_readlane_b32 s7, v254, 46
	s_mul_i32 s5, s14, 0xe00
	s_add_u32 s6, s6, s5
	s_addc_u32 s7, s7, 0
	s_add_u32 s6, s6, 0x1073f600
	s_addc_u32 s7, s7, 0
	s_add_i32 s5, s17, -8
	v_add_u32_e32 v12, s5, v10
	v_mov_b32_e32 v16, 0
	v_mov_b32_e32 v17, 0
	v_mov_b32_e32 v18, 0
	v_mov_b32_e32 v19, 0
	v_mov_b32_e32 v20, 0
	v_mov_b32_e32 v21, 0
	v_mov_b32_e32 v22, 0
	v_mov_b32_e32 v23, 0
	v_mov_b32_e32 v24, 0
	v_mov_b32_e32 v25, 0
	v_mov_b32_e32 v26, 0
	v_mov_b32_e32 v27, 0
	v_mov_b32_e32 v28, 0
	v_mov_b32_e32 v29, 0
	v_mov_b32_e32 v30, 0
	v_mov_b32_e32 v31, 0
	v_mov_b32_e32 v32, 0
	v_mov_b32_e32 v33, 0
	v_mov_b32_e32 v34, 0
	v_mov_b32_e32 v35, 0
	v_mov_b32_e32 v48, v11
	v_cmp_gt_u32_e32 vcc, s15, v12
	s_and_saveexec_b64 s[36:37], vcc
	global_load_dwordx4 v[16:19], v48, s[6:7]
	s_mov_b64 exec, s[36:37]
	v_add_u32_e32 v13, 16, v12
	v_add_u32_e32 v49, 0xe000, v11
	v_cmp_gt_u32_e32 vcc, s15, v13
	s_and_saveexec_b64 s[36:37], vcc
	global_load_dwordx4 v[20:23], v49, s[6:7]
	s_mov_b64 exec, s[36:37]
	v_add_u32_e32 v13, 32, v12
	v_add_u32_e32 v50, 0x1c000, v11
	v_cmp_gt_u32_e32 vcc, s15, v13
	s_and_saveexec_b64 s[36:37], vcc
	global_load_dwordx4 v[24:27], v50, s[6:7]
	s_mov_b64 exec, s[36:37]
	v_add_u32_e32 v13, 48, v12
	v_add_u32_e32 v51, 0x2a000, v11
	v_cmp_gt_u32_e32 vcc, s15, v13
	s_and_saveexec_b64 s[36:37], vcc
	global_load_dwordx4 v[28:31], v51, s[6:7]
	s_mov_b64 exec, s[36:37]
	v_add_u32_e32 v13, 64, v12
	v_add_u32_e32 v52, 0x38000, v11
	v_cmp_gt_u32_e32 vcc, s15, v13
	s_and_saveexec_b64 s[36:37], vcc
	global_load_dwordx4 v[32:35], v52, s[6:7]
	s_mov_b64 exec, s[36:37]
	global_load_dword v60, v9, s[20:21]
	global_load_dword v61, v9, s[20:21] offset:128
	global_load_dword v62, v9, s[20:21] offset:512
	global_load_dword v63, v9, s[20:21] offset:640
	global_load_dword v64, v9, s[20:21] offset:1024
	global_load_dword v65, v9, s[20:21] offset:1152
	global_load_dword v66, v9, s[20:21] offset:1536
	global_load_dword v67, v9, s[20:21] offset:1664
	global_load_dword v68, v9, s[20:21] offset:2048
	global_load_dword v69, v9, s[20:21] offset:2176
	global_load_dword v70, v9, s[20:21] offset:2560
	global_load_dword v71, v9, s[20:21] offset:2688
	global_load_dword v72, v9, s[20:21] offset:3072
	global_load_dword v73, v9, s[20:21] offset:3200
	global_load_dword v74, v9, s[20:21] offset:3584
	global_load_dword v75, v9, s[20:21] offset:3712
	global_load_dword v76, v9, s[38:39]
	global_load_dword v77, v9, s[38:39] offset:128
	global_load_dword v78, v9, s[38:39] offset:512
	global_load_dword v79, v9, s[38:39] offset:640
	global_load_dword v80, v9, s[38:39] offset:1024
	global_load_dword v81, v9, s[38:39] offset:1152
	global_load_dword v82, v9, s[38:39] offset:1536
	global_load_dword v83, v9, s[38:39] offset:1664
	global_load_dword v84, v9, s[38:39] offset:2048
	global_load_dword v85, v9, s[38:39] offset:2176
	global_load_dword v86, v9, s[38:39] offset:2560
	global_load_dword v87, v9, s[38:39] offset:2688
	global_load_dword v88, v9, s[38:39] offset:3072
	global_load_dword v89, v9, s[38:39] offset:3200
	global_load_dword v90, v9, s[38:39] offset:3584
	global_load_dword v91, v9, s[38:39] offset:3712
	global_load_dword v92, v9, s[40:41]
	global_load_dword v93, v9, s[40:41] offset:128
	global_load_dword v94, v9, s[40:41] offset:512
	global_load_dword v95, v9, s[40:41] offset:640
	global_load_dword v96, v9, s[40:41] offset:1024
	global_load_dword v97, v9, s[40:41] offset:1152
	global_load_dword v98, v9, s[40:41] offset:1536
	global_load_dword v99, v9, s[40:41] offset:1664
	global_load_dword v100, v9, s[40:41] offset:2048
	global_load_dword v101, v9, s[40:41] offset:2176
	global_load_dword v102, v9, s[40:41] offset:2560
	global_load_dword v103, v9, s[40:41] offset:2688
	global_load_dword v104, v9, s[40:41] offset:3072
	global_load_dword v105, v9, s[40:41] offset:3200
	global_load_dword v106, v9, s[40:41] offset:3584
	global_load_dword v107, v9, s[40:41] offset:3712
	global_load_dword v108, v9, s[42:43]
	global_load_dword v109, v9, s[42:43] offset:128
	global_load_dword v110, v9, s[42:43] offset:512
	global_load_dword v111, v9, s[42:43] offset:640
	global_load_dword v112, v9, s[42:43] offset:1024
	global_load_dword v113, v9, s[42:43] offset:1152
	global_load_dword v114, v9, s[42:43] offset:1536
	global_load_dword v115, v9, s[42:43] offset:1664
	s_waitcnt vmcnt(56)
	v_lshlrev_b32_e32 v15, 9, v10
	v_lshl_add_u32 v15, v7, 4, v15
	ds_write_b128 v15, v[16:19]
	ds_write_b128 v15, v[20:23] offset:8192
	ds_write_b128 v15, v[24:27] offset:16384
	ds_write_b128 v15, v[28:31] offset:24576
	ds_write_b128 v15, v[32:35] offset:32768
	global_load_dword v116, v9, s[42:43] offset:2048
	global_load_dword v117, v9, s[42:43] offset:2176
	global_load_dword v118, v9, s[42:43] offset:2560
	global_load_dword v119, v9, s[42:43] offset:2688
	global_load_dword v120, v9, s[42:43] offset:3072
	global_load_dword v121, v9, s[42:43] offset:3200
	global_load_dword v122, v9, s[42:43] offset:3584
	global_load_dword v123, v9, s[42:43] offset:3712
	s_waitcnt lgkmcnt(0)
	s_barrier
; DI float bf2f(u16 v) { return __uint_as_float(((unsigned)v) << 16); }
; DI void pool_item(const Params& P, unsigned char* lds, const int l, const int tt, const int tid) {
;     ...
;         const int ch = tid & 255, tg = tid >> 8, g = ch >> 6, w = 2 << g;
;         for (int tk = 0; tk < 32; ++tk) {
;           int tok = tg * 32 + tk, t = t0 + tok;
;           int lo = max(t - (w >> 1), 0), hi = min(t - (w >> 1) + w, n);
;           float s = 0.f;
;           for (int q = lo; q < hi; ++q) s += bf2f(U[(q - t0 + 8) * 256 + ch]);
;           float mean = s / (float)(hi - lo);
;           Y[tok * 256 + ch] = mean - bf2f(U[(tok + 8) * 256 + ch]);
	s_lshl_b32 s5, 1, s3
	s_lshl_b32 s18, s4, 5
	s_add_i32 s18, s18, 8
	s_sub_i32 s38, s18, s5
	s_lshl_b32 s38, s38, 9
	s_lshl_b32 s18, s18, 9
	v_and_b32_e32 v10, 0xff, v6
	v_lshlrev_b32_e32 v10, 1, v10
	v_add_u32_e32 v11, s38, v10
	v_add_u32_e32 v12, s18, v10
	ds_read_u16 v124, v11
	ds_read_u16 v125, v11 offset:512
	ds_read_u16 v126, v11 offset:1024
	ds_read_u16 v127, v11 offset:1536
	ds_read_u16 v128, v11 offset:2048
	ds_read_u16 v129, v11 offset:2560
	ds_read_u16 v130, v11 offset:3072
	ds_read_u16 v131, v11 offset:3584
	ds_read_u16 v132, v11 offset:4096
	ds_read_u16 v133, v11 offset:4608
	ds_read_u16 v134, v11 offset:5120
	ds_read_u16 v135, v11 offset:5632
	ds_read_u16 v136, v11 offset:6144
	ds_read_u16 v137, v11 offset:6656
	ds_read_u16 v138, v11 offset:7168
	ds_read_u16 v139, v11 offset:7680
	ds_read_u16 v140, v11 offset:8192
	ds_read_u16 v141, v11 offset:8704
	ds_read_u16 v142, v11 offset:9216
	ds_read_u16 v143, v11 offset:9728
	ds_read_u16 v144, v11 offset:10240
	ds_read_u16 v145, v11 offset:10752
	ds_read_u16 v146, v11 offset:11264
	ds_read_u16 v147, v11 offset:11776
	ds_read_u16 v148, v11 offset:12288
	ds_read_u16 v149, v11 offset:12800
	ds_read_u16 v150, v11 offset:13312
	ds_read_u16 v151, v11 offset:13824
	ds_read_u16 v152, v11 offset:14336
	ds_read_u16 v153, v11 offset:14848
	ds_read_u16 v154, v11 offset:15360
	ds_read_u16 v155, v11 offset:15872
	ds_read_u16 v156, v11 offset:16384
	ds_read_u16 v157, v11 offset:16896
	ds_read_u16 v158, v11 offset:17408
	ds_read_u16 v159, v11 offset:17920
	ds_read_u16 v160, v11 offset:18432
	ds_read_u16 v161, v11 offset:18944
	ds_read_u16 v162, v11 offset:19456
	ds_read_u16 v163, v11 offset:19968
	ds_read_u16 v164, v11 offset:20480
	ds_read_u16 v165, v11 offset:20992
	ds_read_u16 v166, v11 offset:21504
	ds_read_u16 v167, v11 offset:22016
	ds_read_u16 v168, v11 offset:22528
	ds_read_u16 v169, v11 offset:23040
	ds_read_u16 v170, v11 offset:23552
	ds_read_u16 v16, v12
	ds_read_u16 v17, v12 offset:512
	ds_read_u16 v18, v12 offset:1024
	ds_read_u16 v19, v12 offset:1536
	ds_read_u16 v20, v12 offset:2048
	ds_read_u16 v21, v12 offset:2560
	ds_read_u16 v22, v12 offset:3072
	ds_read_u16 v23, v12 offset:3584
	ds_read_u16 v24, v12 offset:4096
	ds_read_u16 v25, v12 offset:4608
	ds_read_u16 v26, v12 offset:5120
	ds_read_u16 v27, v12 offset:5632
	ds_read_u16 v28, v12 offset:6144
	ds_read_u16 v29, v12 offset:6656
	ds_read_u16 v30, v12 offset:7168
	ds_read_u16 v31, v12 offset:7680
	ds_read_u16 v32, v12 offset:8192
	ds_read_u16 v33, v12 offset:8704
	ds_read_u16 v34, v12 offset:9216
	ds_read_u16 v35, v12 offset:9728
	ds_read_u16 v36, v12 offset:10240
	ds_read_u16 v37, v12 offset:10752
	ds_read_u16 v38, v12 offset:11264
	ds_read_u16 v39, v12 offset:11776
	ds_read_u16 v40, v12 offset:12288
	ds_read_u16 v41, v12 offset:12800
	ds_read_u16 v42, v12 offset:13312
	ds_read_u16 v43, v12 offset:13824
	ds_read_u16 v44, v12 offset:14336
	ds_read_u16 v45, v12 offset:14848
	ds_read_u16 v46, v12 offset:15360
	ds_read_u16 v47, v12 offset:15872
	s_add_i32 s39, s3, 1
	s_lshl_b32 s39, s39, 23
	s_add_i32 s41, s39, 0x3f800000
	s_sub_i32 s42, 0x3f800000, s39
	s_waitcnt lgkmcnt(0)
	v_lshlrev_b32_e32 v124, 16, v124
	v_lshlrev_b32_e32 v125, 16, v125
	v_lshlrev_b32_e32 v126, 16, v126
	v_lshlrev_b32_e32 v127, 16, v127
	v_lshlrev_b32_e32 v128, 16, v128
	v_lshlrev_b32_e32 v129, 16, v129
	v_lshlrev_b32_e32 v130, 16, v130
	v_lshlrev_b32_e32 v131, 16, v131
	v_lshlrev_b32_e32 v132, 16, v132
	v_lshlrev_b32_e32 v133, 16, v133
	v_lshlrev_b32_e32 v134, 16, v134
	v_lshlrev_b32_e32 v135, 16, v135
	v_lshlrev_b32_e32 v136, 16, v136
	v_lshlrev_b32_e32 v137, 16, v137
	v_lshlrev_b32_e32 v138, 16, v138
	v_lshlrev_b32_e32 v139, 16, v139
	v_lshlrev_b32_e32 v140, 16, v140
	v_lshlrev_b32_e32 v141, 16, v141
	v_lshlrev_b32_e32 v142, 16, v142
	v_lshlrev_b32_e32 v143, 16, v143
	v_lshlrev_b32_e32 v144, 16, v144
	v_lshlrev_b32_e32 v145, 16, v145
	v_lshlrev_b32_e32 v146, 16, v146
	v_lshlrev_b32_e32 v147, 16, v147
	v_lshlrev_b32_e32 v148, 16, v148
	v_lshlrev_b32_e32 v149, 16, v149
	v_lshlrev_b32_e32 v150, 16, v150
	v_lshlrev_b32_e32 v151, 16, v151
	v_lshlrev_b32_e32 v152, 16, v152
	v_lshlrev_b32_e32 v153, 16, v153
	v_lshlrev_b32_e32 v154, 16, v154
	v_lshlrev_b32_e32 v155, 16, v155
	v_lshlrev_b32_e32 v156, 16, v156
	v_lshlrev_b32_e32 v157, 16, v157
	v_lshlrev_b32_e32 v158, 16, v158
	v_lshlrev_b32_e32 v159, 16, v159
	v_lshlrev_b32_e32 v160, 16, v160
	v_lshlrev_b32_e32 v161, 16, v161
	v_lshlrev_b32_e32 v162, 16, v162
	v_lshlrev_b32_e32 v163, 16, v163
	v_lshlrev_b32_e32 v164, 16, v164
	v_lshlrev_b32_e32 v165, 16, v165
	v_lshlrev_b32_e32 v166, 16, v166
	v_lshlrev_b32_e32 v167, 16, v167
	v_lshlrev_b32_e32 v168, 16, v168
	v_lshlrev_b32_e32 v169, 16, v169
	v_lshlrev_b32_e32 v170, 16, v170
	v_lshlrev_b32_e32 v16, 16, v16
	v_lshlrev_b32_e32 v17, 16, v17
	v_lshlrev_b32_e32 v18, 16, v18
	v_lshlrev_b32_e32 v19, 16, v19
	v_lshlrev_b32_e32 v20, 16, v20
	v_lshlrev_b32_e32 v21, 16, v21
	v_lshlrev_b32_e32 v22, 16, v22
	v_lshlrev_b32_e32 v23, 16, v23
	v_lshlrev_b32_e32 v24, 16, v24
	v_lshlrev_b32_e32 v25, 16, v25
	v_lshlrev_b32_e32 v26, 16, v26
	v_lshlrev_b32_e32 v27, 16, v27
	v_lshlrev_b32_e32 v28, 16, v28
	v_lshlrev_b32_e32 v29, 16, v29
	v_lshlrev_b32_e32 v30, 16, v30
	v_lshlrev_b32_e32 v31, 16, v31
	v_lshlrev_b32_e32 v32, 16, v32
	v_lshlrev_b32_e32 v33, 16, v33
	v_lshlrev_b32_e32 v34, 16, v34
	v_lshlrev_b32_e32 v35, 16, v35
	v_lshlrev_b32_e32 v36, 16, v36
	v_lshlrev_b32_e32 v37, 16, v37
	v_lshlrev_b32_e32 v38, 16, v38
	v_lshlrev_b32_e32 v39, 16, v39
	v_lshlrev_b32_e32 v40, 16, v40
	v_lshlrev_b32_e32 v41, 16, v41
	v_lshlrev_b32_e32 v42, 16, v42
	v_lshlrev_b32_e32 v43, 16, v43
; DI float bf2f(u16 v) { return __uint_as_float(((unsigned)v) << 16); }
; DI void pool_item(const Params& P, unsigned char* lds, const int l, const int tt, const int tid) {
;     ...
;         const int ch = tid & 255, tg = tid >> 8, g = ch >> 6, w = 2 << g;
;         for (int tk = 0; tk < 32; ++tk) {
;           int tok = tg * 32 + tk, t = t0 + tok;
;           int lo = max(t - (w >> 1), 0), hi = min(t - (w >> 1) + w, n);
;           float s = 0.f;
;           for (int q = lo; q < hi; ++q) s += bf2f(U[(q - t0 + 8) * 256 + ch]);
;           float mean = s / (float)(hi - lo);
;           Y[tok * 256 + ch] = mean - bf2f(U[(tok + 8) * 256 + ch]);
;         }
	v_lshlrev_b32_e32 v44, 16, v44
	v_lshlrev_b32_e32 v45, 16, v45
	v_lshlrev_b32_e32 v46, 16, v46
	v_lshlrev_b32_e32 v47, 16, v47
	v_add_f32_e32 v124, v124, v125
	v_add_f32_e32 v125, v125, v126
	v_add_f32_e32 v126, v126, v127
	v_add_f32_e32 v127, v127, v128
	v_add_f32_e32 v128, v128, v129
	v_add_f32_e32 v129, v129, v130
	v_add_f32_e32 v130, v130, v131
	v_add_f32_e32 v131, v131, v132
	v_add_f32_e32 v132, v132, v133
	v_add_f32_e32 v133, v133, v134
	v_add_f32_e32 v134, v134, v135
	v_add_f32_e32 v135, v135, v136
	v_add_f32_e32 v136, v136, v137
	v_add_f32_e32 v137, v137, v138
	v_add_f32_e32 v138, v138, v139
	v_add_f32_e32 v139, v139, v140
	v_add_f32_e32 v140, v140, v141
	v_add_f32_e32 v141, v141, v142
	v_add_f32_e32 v142, v142, v143
	v_add_f32_e32 v143, v143, v144
	v_add_f32_e32 v144, v144, v145
	v_add_f32_e32 v145, v145, v146
	v_add_f32_e32 v146, v146, v147
	v_add_f32_e32 v147, v147, v148
	v_add_f32_e32 v148, v148, v149
	v_add_f32_e32 v149, v149, v150
	v_add_f32_e32 v150, v150, v151
	v_add_f32_e32 v151, v151, v152
	v_add_f32_e32 v152, v152, v153
	v_add_f32_e32 v153, v153, v154
	v_add_f32_e32 v154, v154, v155
	v_add_f32_e32 v155, v155, v156
	v_add_f32_e32 v156, v156, v157
	v_add_f32_e32 v157, v157, v158
	v_add_f32_e32 v158, v158, v159
	v_add_f32_e32 v159, v159, v160
	v_add_f32_e32 v160, v160, v161
	v_add_f32_e32 v161, v161, v162
	v_add_f32_e32 v162, v162, v163
	v_add_f32_e32 v163, v163, v164
	v_add_f32_e32 v164, v164, v165
	v_add_f32_e32 v165, v165, v166
	v_add_f32_e32 v166, v166, v167
	v_add_f32_e32 v167, v167, v168
	v_add_f32_e32 v168, v168, v169
	v_add_f32_e32 v169, v169, v170
	s_cmp_eq_u32 s3, 0
	s_cbranch_scc1 .Lpool_tree_done
	v_add_f32_e32 v124, v124, v126
	v_add_f32_e32 v125, v125, v127
	v_add_f32_e32 v126, v126, v128
	v_add_f32_e32 v127, v127, v129
	v_add_f32_e32 v128, v128, v130
	v_add_f32_e32 v129, v129, v131
	v_add_f32_e32 v130, v130, v132
	v_add_f32_e32 v131, v131, v133
	v_add_f32_e32 v132, v132, v134
	v_add_f32_e32 v133, v133, v135
	v_add_f32_e32 v134, v134, v136
	v_add_f32_e32 v135, v135, v137
	v_add_f32_e32 v136, v136, v138
	v_add_f32_e32 v137, v137, v139
	v_add_f32_e32 v138, v138, v140
	v_add_f32_e32 v139, v139, v141
	v_add_f32_e32 v140, v140, v142
	v_add_f32_e32 v141, v141, v143
	v_add_f32_e32 v142, v142, v144
	v_add_f32_e32 v143, v143, v145
	v_add_f32_e32 v144, v144, v146
	v_add_f32_e32 v145, v145, v147
	v_add_f32_e32 v146, v146, v148
	v_add_f32_e32 v147, v147, v149
	v_add_f32_e32 v148, v148, v150
	v_add_f32_e32 v149, v149, v151
	v_add_f32_e32 v150, v150, v152
	v_add_f32_e32 v151, v151, v153
	v_add_f32_e32 v152, v152, v154
	v_add_f32_e32 v153, v153, v155
	v_add_f32_e32 v154, v154, v156
	v_add_f32_e32 v155, v155, v157
	v_add_f32_e32 v156, v156, v158
	v_add_f32_e32 v157, v157, v159
	v_add_f32_e32 v158, v158, v160
	v_add_f32_e32 v159, v159, v161
	v_add_f32_e32 v160, v160, v162
	v_add_f32_e32 v161, v161, v163
	v_add_f32_e32 v162, v162, v164
	v_add_f32_e32 v163, v163, v165
	v_add_f32_e32 v164, v164, v166
	v_add_f32_e32 v165, v165, v167
	v_add_f32_e32 v166, v166, v168
	v_add_f32_e32 v167, v167, v169
	s_cmp_eq_u32 s3, 1
	s_cbranch_scc1 .Lpool_tree_done
	v_add_f32_e32 v124, v124, v128
	v_add_f32_e32 v125, v125, v129
	v_add_f32_e32 v126, v126, v130
	v_add_f32_e32 v127, v127, v131
	v_add_f32_e32 v128, v128, v132
	v_add_f32_e32 v129, v129, v133
	v_add_f32_e32 v130, v130, v134
	v_add_f32_e32 v131, v131, v135
	v_add_f32_e32 v132, v132, v136
	v_add_f32_e32 v133, v133, v137
	v_add_f32_e32 v134, v134, v138
	v_add_f32_e32 v135, v135, v139
	v_add_f32_e32 v136, v136, v140
	v_add_f32_e32 v137, v137, v141
	v_add_f32_e32 v138, v138, v142
	v_add_f32_e32 v139, v139, v143
	v_add_f32_e32 v140, v140, v144
	v_add_f32_e32 v141, v141, v145
	v_add_f32_e32 v142, v142, v146
	v_add_f32_e32 v143, v143, v147
	v_add_f32_e32 v144, v144, v148
	v_add_f32_e32 v145, v145, v149
	v_add_f32_e32 v146, v146, v150
	v_add_f32_e32 v147, v147, v151
	v_add_f32_e32 v148, v148, v152
	v_add_f32_e32 v149, v149, v153
	v_add_f32_e32 v150, v150, v154
	v_add_f32_e32 v151, v151, v155
	v_add_f32_e32 v152, v152, v156
	v_add_f32_e32 v153, v153, v157
	v_add_f32_e32 v154, v154, v158
	v_add_f32_e32 v155, v155, v159
	v_add_f32_e32 v156, v156, v160
	v_add_f32_e32 v157, v157, v161
	v_add_f32_e32 v158, v158, v162
	v_add_f32_e32 v159, v159, v163
	v_add_f32_e32 v160, v160, v164
	v_add_f32_e32 v161, v161, v165
	v_add_f32_e32 v162, v162, v166
	v_add_f32_e32 v163, v163, v167
	s_cmp_eq_u32 s3, 2
	s_cbranch_scc1 .Lpool_tree_done
	v_add_f32_e32 v124, v124, v132
	v_add_f32_e32 v125, v125, v133
	v_add_f32_e32 v126, v126, v134
	v_add_f32_e32 v127, v127, v135
	v_add_f32_e32 v128, v128, v136
	v_add_f32_e32 v129, v129, v137
	v_add_f32_e32 v130, v130, v138
	v_add_f32_e32 v131, v131, v139
	v_add_f32_e32 v132, v132, v140
	v_add_f32_e32 v133, v133, v141
	v_add_f32_e32 v134, v134, v142
	v_add_f32_e32 v135, v135, v143
	v_add_f32_e32 v136, v136, v144
	v_add_f32_e32 v137, v137, v145
	v_add_f32_e32 v138, v138, v146
	v_add_f32_e32 v139, v139, v147
	v_add_f32_e32 v140, v140, v148
	v_add_f32_e32 v141, v141, v149
	v_add_f32_e32 v142, v142, v150
	v_add_f32_e32 v143, v143, v151
	v_add_f32_e32 v144, v144, v152
	v_add_f32_e32 v145, v145, v153
	v_add_f32_e32 v146, v146, v154
	v_add_f32_e32 v147, v147, v155
	v_add_f32_e32 v148, v148, v156
	v_add_f32_e32 v149, v149, v157
	v_add_f32_e32 v150, v150, v158
	v_add_f32_e32 v151, v151, v159
	v_add_f32_e32 v152, v152, v160
	v_add_f32_e32 v153, v153, v161
	v_add_f32_e32 v154, v154, v162
	v_add_f32_e32 v155, v155, v163
; DI float bf2f(u16 v) { return __uint_as_float(((unsigned)v) << 16); }
; DI void pool_item(const Params& P, unsigned char* lds, const int l, const int tt, const int tid) {
;     ...
;         for (int tk = 0; tk < 32; ++tk) {
;           int tok = tg * 32 + tk, t = t0 + tok;
;           int lo = max(t - (w >> 1), 0), hi = min(t - (w >> 1) + w, n);
;           float s = 0.f;
;           for (int q = lo; q < hi; ++q) s += bf2f(U[(q - t0 + 8) * 256 + ch]);
;           float mean = s / (float)(hi - lo);
;           Y[tok * 256 + ch] = mean - bf2f(U[(tok + 8) * 256 + ch]);
.Lpool_tree_done:
	s_lshl_b32 s40, s5, 1
	s_or_b32 s38, s17, s4
	s_cmp_lg_u32 s38, 0
	s_cbranch_scc1 .Lpool_no_start
	s_add_i32 s39, s5, 0
	s_min_u32 s39, s39, s40
	v_cvt_f32_u32_e32 v13, s39
	v_div_scale_f32 v48, s[44:45], v13, v13, v124
	v_rcp_f32_e32 v49, v48
	s_nop 0
	v_fma_f32 v50, -v48, v49, 1.0
	v_fmac_f32_e32 v49, v50, v49
	v_div_scale_f32 v50, vcc, v124, v13, v124
	v_mul_f32_e32 v51, v50, v49
	v_fma_f32 v52, -v48, v51, v50
	v_fmac_f32_e32 v51, v52, v49
	v_fma_f32 v48, -v48, v51, v50
	v_div_fmas_f32 v48, v48, v49, v51
	v_div_fixup_f32 v124, v48, v13, v124
	v_mul_f32_e32 v124, s41, v124
	s_add_i32 s39, s5, 1
	s_min_u32 s39, s39, s40
	v_cvt_f32_u32_e32 v13, s39
	v_div_scale_f32 v48, s[44:45], v13, v13, v125
	v_rcp_f32_e32 v49, v48
	s_nop 0
	v_fma_f32 v50, -v48, v49, 1.0
	v_fmac_f32_e32 v49, v50, v49
	v_div_scale_f32 v50, vcc, v125, v13, v125
	v_mul_f32_e32 v51, v50, v49
	v_fma_f32 v52, -v48, v51, v50
	v_fmac_f32_e32 v51, v52, v49
	v_fma_f32 v48, -v48, v51, v50
	v_div_fmas_f32 v48, v48, v49, v51
	v_div_fixup_f32 v125, v48, v13, v125
	v_mul_f32_e32 v125, s41, v125
	s_add_i32 s39, s5, 2
	s_min_u32 s39, s39, s40
	v_cvt_f32_u32_e32 v13, s39
	v_div_scale_f32 v48, s[44:45], v13, v13, v126
	v_rcp_f32_e32 v49, v48
	s_nop 0
	v_fma_f32 v50, -v48, v49, 1.0
	v_fmac_f32_e32 v49, v50, v49
	v_div_scale_f32 v50, vcc, v126, v13, v126
	v_mul_f32_e32 v51, v50, v49
	v_fma_f32 v52, -v48, v51, v50
	v_fmac_f32_e32 v51, v52, v49
	v_fma_f32 v48, -v48, v51, v50
	v_div_fmas_f32 v48, v48, v49, v51
	v_div_fixup_f32 v126, v48, v13, v126
	v_mul_f32_e32 v126, s41, v126
	s_add_i32 s39, s5, 3
	s_min_u32 s39, s39, s40
	v_cvt_f32_u32_e32 v13, s39
	v_div_scale_f32 v48, s[44:45], v13, v13, v127
	v_rcp_f32_e32 v49, v48
	s_nop 0
	v_fma_f32 v50, -v48, v49, 1.0
	v_fmac_f32_e32 v49, v50, v49
	v_div_scale_f32 v50, vcc, v127, v13, v127
	v_mul_f32_e32 v51, v50, v49
	v_fma_f32 v52, -v48, v51, v50
	v_fmac_f32_e32 v51, v52, v49
	v_fma_f32 v48, -v48, v51, v50
	v_div_fmas_f32 v48, v48, v49, v51
	v_div_fixup_f32 v127, v48, v13, v127
	v_mul_f32_e32 v127, s41, v127
	s_add_i32 s39, s5, 4
	s_min_u32 s39, s39, s40
	v_cvt_f32_u32_e32 v13, s39
	v_div_scale_f32 v48, s[44:45], v13, v13, v128
	v_rcp_f32_e32 v49, v48
	s_nop 0
	v_fma_f32 v50, -v48, v49, 1.0
	v_fmac_f32_e32 v49, v50, v49
	v_div_scale_f32 v50, vcc, v128, v13, v128
	v_mul_f32_e32 v51, v50, v49
	v_fma_f32 v52, -v48, v51, v50
	v_fmac_f32_e32 v51, v52, v49
	v_fma_f32 v48, -v48, v51, v50
	v_div_fmas_f32 v48, v48, v49, v51
	v_div_fixup_f32 v128, v48, v13, v128
	v_mul_f32_e32 v128, s41, v128
	s_add_i32 s39, s5, 5
	s_min_u32 s39, s39, s40
	v_cvt_f32_u32_e32 v13, s39
	v_div_scale_f32 v48, s[44:45], v13, v13, v129
	v_rcp_f32_e32 v49, v48
	s_nop 0
	v_fma_f32 v50, -v48, v49, 1.0
	v_fmac_f32_e32 v49, v50, v49
	v_div_scale_f32 v50, vcc, v129, v13, v129
	v_mul_f32_e32 v51, v50, v49
	v_fma_f32 v52, -v48, v51, v50
	v_fmac_f32_e32 v51, v52, v49
	v_fma_f32 v48, -v48, v51, v50
	v_div_fmas_f32 v48, v48, v49, v51
	v_div_fixup_f32 v129, v48, v13, v129
	v_mul_f32_e32 v129, s41, v129
	s_add_i32 s39, s5, 6
	s_min_u32 s39, s39, s40
	v_cvt_f32_u32_e32 v13, s39
	v_div_scale_f32 v48, s[44:45], v13, v13, v130
	v_rcp_f32_e32 v49, v48
	s_nop 0
	v_fma_f32 v50, -v48, v49, 1.0
	v_fmac_f32_e32 v49, v50, v49
	v_div_scale_f32 v50, vcc, v130, v13, v130
	v_mul_f32_e32 v51, v50, v49
	v_fma_f32 v52, -v48, v51, v50
	v_fmac_f32_e32 v51, v52, v49
	v_fma_f32 v48, -v48, v51, v50
	v_div_fmas_f32 v48, v48, v49, v51
	v_div_fixup_f32 v130, v48, v13, v130
	v_mul_f32_e32 v130, s41, v130
	s_add_i32 s39, s5, 7
	s_min_u32 s39, s39, s40
	v_cvt_f32_u32_e32 v13, s39
	v_div_scale_f32 v48, s[44:45], v13, v13, v131
	v_rcp_f32_e32 v49, v48
	s_nop 0
	v_fma_f32 v50, -v48, v49, 1.0
	v_fmac_f32_e32 v49, v50, v49
	v_div_scale_f32 v50, vcc, v131, v13, v131
	v_mul_f32_e32 v51, v50, v49
	v_fma_f32 v52, -v48, v51, v50
	v_fmac_f32_e32 v51, v52, v49
	v_fma_f32 v48, -v48, v51, v50
	v_div_fmas_f32 v48, v48, v49, v51
	v_div_fixup_f32 v131, v48, v13, v131
	v_mul_f32_e32 v131, s41, v131
.Lpool_no_start:
	s_add_i32 s38, s17, 64
	s_sub_i32 s38, s15, s38
	s_xor_b32 s39, s4, 1
	s_or_b32 s38, s38, s39
	s_cmp_lg_u32 s38, 0
	s_cbranch_scc1 .Lpool_no_end
	s_add_i32 s39, s5, 8
	s_min_u32 s39, s39, s40
	v_cvt_f32_u32_e32 v13, s39
	v_div_scale_f32 v48, s[44:45], v13, v13, v148
	v_rcp_f32_e32 v49, v48
	s_nop 0
	v_fma_f32 v50, -v48, v49, 1.0
	v_fmac_f32_e32 v49, v50, v49
	v_div_scale_f32 v50, vcc, v148, v13, v148
	v_mul_f32_e32 v51, v50, v49
	v_fma_f32 v52, -v48, v51, v50
	v_fmac_f32_e32 v51, v52, v49
	v_fma_f32 v48, -v48, v51, v50
	v_div_fmas_f32 v48, v48, v49, v51
	v_div_fixup_f32 v148, v48, v13, v148
	v_mul_f32_e32 v148, s41, v148
	s_add_i32 s39, s5, 7
	s_min_u32 s39, s39, s40
	v_cvt_f32_u32_e32 v13, s39
	v_div_scale_f32 v48, s[44:45], v13, v13, v149
	v_rcp_f32_e32 v49, v48
	s_nop 0
	v_fma_f32 v50, -v48, v49, 1.0
	v_fmac_f32_e32 v49, v50, v49
	v_div_scale_f32 v50, vcc, v149, v13, v149
	v_mul_f32_e32 v51, v50, v49
	v_fma_f32 v52, -v48, v51, v50
	v_fmac_f32_e32 v51, v52, v49
	v_fma_f32 v48, -v48, v51, v50
	v_div_fmas_f32 v48, v48, v49, v51
	v_div_fixup_f32 v149, v48, v13, v149
	v_mul_f32_e32 v149, s41, v149
	s_add_i32 s39, s5, 6
	s_min_u32 s39, s39, s40
	v_cvt_f32_u32_e32 v13, s39
	v_div_scale_f32 v48, s[44:45], v13, v13, v150
	v_rcp_f32_e32 v49, v48
	s_nop 0
	v_fma_f32 v50, -v48, v49, 1.0
	v_fmac_f32_e32 v49, v50, v49
	v_div_scale_f32 v50, vcc, v150, v13, v150
	v_mul_f32_e32 v51, v50, v49
	v_fma_f32 v52, -v48, v51, v50
	v_fmac_f32_e32 v51, v52, v49
	v_fma_f32 v48, -v48, v51, v50
	v_div_fmas_f32 v48, v48, v49, v51
	v_div_fixup_f32 v150, v48, v13, v150
	v_mul_f32_e32 v150, s41, v150
	s_add_i32 s39, s5, 5
	s_min_u32 s39, s39, s40
; DI float bf2f(u16 v) { return __uint_as_float(((unsigned)v) << 16); }
; DI void pool_item(const Params& P, unsigned char* lds, const int l, const int tt, const int tid) {
;     ...
;           Y[tok * 256 + ch] = mean - bf2f(U[(tok + 8) * 256 + ch]);
;         }
;       }
;       __syncthreads();
;       {
;         const int dcol = tid & 255, tg = tid >> 8, g = dcol >> 6, d = dcol & 63;
;         const float* pw = P.pool_w + ((size_t)(l * 4 + g) * 64) * 64 + d;
;         float acc[32];
; #pragma unroll
;         for (int tk = 0; tk < 32; ++tk) acc[tk] = 0.f;
;         for (int c4 = 0; c4 < 16; ++c4) {
;           float w0 = pw[(c4 * 4 + 0) * 64], w1 = pw[(c4 * 4 + 1) * 64], w2 = pw[(c4 * 4 + 2) * 64], w3 = pw[(c4 * 4 + 3) * 64];
; #pragma unroll
;           for (int tk = 0; tk < 32; ++tk) {
;             float4 yv = *(const float4*)(Y + (tg * 32 + tk) * 256 + g * 64 + c4 * 4);
;             acc[tk] += yv.x * w0 + yv.y * w1 + yv.z * w2 + yv.w * w3;
;           }
;         }
;         const float psc = P.pool_scale[l * 256 + dcol];
	v_cvt_f32_u32_e32 v13, s39
	v_div_scale_f32 v48, s[44:45], v13, v13, v151
	v_rcp_f32_e32 v49, v48
	s_nop 0
	v_fma_f32 v50, -v48, v49, 1.0
	v_fmac_f32_e32 v49, v50, v49
	v_div_scale_f32 v50, vcc, v151, v13, v151
	v_mul_f32_e32 v51, v50, v49
	v_fma_f32 v52, -v48, v51, v50
	v_fmac_f32_e32 v51, v52, v49
	v_fma_f32 v48, -v48, v51, v50
	v_div_fmas_f32 v48, v48, v49, v51
	v_div_fixup_f32 v151, v48, v13, v151
	v_mul_f32_e32 v151, s41, v151
	s_add_i32 s39, s5, 4
	s_min_u32 s39, s39, s40
	v_cvt_f32_u32_e32 v13, s39
	v_div_scale_f32 v48, s[44:45], v13, v13, v152
	v_rcp_f32_e32 v49, v48
	s_nop 0
	v_fma_f32 v50, -v48, v49, 1.0
	v_fmac_f32_e32 v49, v50, v49
	v_div_scale_f32 v50, vcc, v152, v13, v152
	v_mul_f32_e32 v51, v50, v49
	v_fma_f32 v52, -v48, v51, v50
	v_fmac_f32_e32 v51, v52, v49
	v_fma_f32 v48, -v48, v51, v50
	v_div_fmas_f32 v48, v48, v49, v51
	v_div_fixup_f32 v152, v48, v13, v152
	v_mul_f32_e32 v152, s41, v152
	s_add_i32 s39, s5, 3
	s_min_u32 s39, s39, s40
	v_cvt_f32_u32_e32 v13, s39
	v_div_scale_f32 v48, s[44:45], v13, v13, v153
	v_rcp_f32_e32 v49, v48
	s_nop 0
	v_fma_f32 v50, -v48, v49, 1.0
	v_fmac_f32_e32 v49, v50, v49
	v_div_scale_f32 v50, vcc, v153, v13, v153
	v_mul_f32_e32 v51, v50, v49
	v_fma_f32 v52, -v48, v51, v50
	v_fmac_f32_e32 v51, v52, v49
	v_fma_f32 v48, -v48, v51, v50
	v_div_fmas_f32 v48, v48, v49, v51
	v_div_fixup_f32 v153, v48, v13, v153
	v_mul_f32_e32 v153, s41, v153
	s_add_i32 s39, s5, 2
	s_min_u32 s39, s39, s40
	v_cvt_f32_u32_e32 v13, s39
	v_div_scale_f32 v48, s[44:45], v13, v13, v154
	v_rcp_f32_e32 v49, v48
	s_nop 0
	v_fma_f32 v50, -v48, v49, 1.0
	v_fmac_f32_e32 v49, v50, v49
	v_div_scale_f32 v50, vcc, v154, v13, v154
	v_mul_f32_e32 v51, v50, v49
	v_fma_f32 v52, -v48, v51, v50
	v_fmac_f32_e32 v51, v52, v49
	v_fma_f32 v48, -v48, v51, v50
	v_div_fmas_f32 v48, v48, v49, v51
	v_div_fixup_f32 v154, v48, v13, v154
	v_mul_f32_e32 v154, s41, v154
	s_add_i32 s39, s5, 1
	s_min_u32 s39, s39, s40
	v_cvt_f32_u32_e32 v13, s39
	v_div_scale_f32 v48, s[44:45], v13, v13, v155
	v_rcp_f32_e32 v49, v48
	s_nop 0
	v_fma_f32 v50, -v48, v49, 1.0
	v_fmac_f32_e32 v49, v50, v49
	v_div_scale_f32 v50, vcc, v155, v13, v155
	v_mul_f32_e32 v51, v50, v49
	v_fma_f32 v52, -v48, v51, v50
	v_fmac_f32_e32 v51, v52, v49
	v_fma_f32 v48, -v48, v51, v50
	v_div_fmas_f32 v48, v48, v49, v51
	v_div_fixup_f32 v155, v48, v13, v155
	v_mul_f32_e32 v155, s41, v155
.Lpool_no_end:
	v_mul_f32_e32 v124, s42, v124
	v_sub_f32_e32 v124, v124, v16
	v_mul_f32_e32 v125, s42, v125
	v_sub_f32_e32 v125, v125, v17
	v_mul_f32_e32 v126, s42, v126
	v_sub_f32_e32 v126, v126, v18
	v_mul_f32_e32 v127, s42, v127
	v_sub_f32_e32 v127, v127, v19
	v_mul_f32_e32 v128, s42, v128
	v_sub_f32_e32 v128, v128, v20
	v_mul_f32_e32 v129, s42, v129
	v_sub_f32_e32 v129, v129, v21
	v_mul_f32_e32 v130, s42, v130
	v_sub_f32_e32 v130, v130, v22
	v_mul_f32_e32 v131, s42, v131
	v_sub_f32_e32 v131, v131, v23
	v_mul_f32_e32 v132, s42, v132
	v_sub_f32_e32 v132, v132, v24
	v_mul_f32_e32 v133, s42, v133
	v_sub_f32_e32 v133, v133, v25
	v_mul_f32_e32 v134, s42, v134
	v_sub_f32_e32 v134, v134, v26
	v_mul_f32_e32 v135, s42, v135
	v_sub_f32_e32 v135, v135, v27
	v_mul_f32_e32 v136, s42, v136
	v_sub_f32_e32 v136, v136, v28
	v_mul_f32_e32 v137, s42, v137
	v_sub_f32_e32 v137, v137, v29
	v_mul_f32_e32 v138, s42, v138
	v_sub_f32_e32 v138, v138, v30
	v_mul_f32_e32 v139, s42, v139
	v_sub_f32_e32 v139, v139, v31
	v_mul_f32_e32 v140, s42, v140
	v_sub_f32_e32 v140, v140, v32
	v_mul_f32_e32 v141, s42, v141
	v_sub_f32_e32 v141, v141, v33
	v_mul_f32_e32 v142, s42, v142
	v_sub_f32_e32 v142, v142, v34
	v_mul_f32_e32 v143, s42, v143
	v_sub_f32_e32 v143, v143, v35
	v_mul_f32_e32 v144, s42, v144
	v_sub_f32_e32 v144, v144, v36
	v_mul_f32_e32 v145, s42, v145
	v_sub_f32_e32 v145, v145, v37
	v_mul_f32_e32 v146, s42, v146
	v_sub_f32_e32 v146, v146, v38
	v_mul_f32_e32 v147, s42, v147
	v_sub_f32_e32 v147, v147, v39
	v_mul_f32_e32 v148, s42, v148
	v_sub_f32_e32 v148, v148, v40
	v_mul_f32_e32 v149, s42, v149
	v_sub_f32_e32 v149, v149, v41
	v_mul_f32_e32 v150, s42, v150
	v_sub_f32_e32 v150, v150, v42
	v_mul_f32_e32 v151, s42, v151
	v_sub_f32_e32 v151, v151, v43
	v_mul_f32_e32 v152, s42, v152
	v_sub_f32_e32 v152, v152, v44
	v_mul_f32_e32 v153, s42, v153
	v_sub_f32_e32 v153, v153, v45
	v_mul_f32_e32 v154, s42, v154
	v_sub_f32_e32 v154, v154, v46
	v_mul_f32_e32 v155, s42, v155
	v_sub_f32_e32 v155, v155, v47
	s_mul_i32 s38, s2, 0x2400
	s_add_i32 s38, s38, 0xa000
	v_and_b32_e32 v10, 63, v6
	v_mul_u32_u24_e32 v11, 0x90, v10
	v_add_u32_e32 v11, s38, v11
	ds_write_b128 v11, v[124:127]
	ds_write_b128 v11, v[128:131] offset:16
	ds_write_b128 v11, v[132:135] offset:32
	ds_write_b128 v11, v[136:139] offset:48
	ds_write_b128 v11, v[140:143] offset:64
	ds_write_b128 v11, v[144:147] offset:80
	ds_write_b128 v11, v[148:151] offset:96
	ds_write_b128 v11, v[152:155] offset:112
	v_mul_u32_u24_e32 v12, 0x90, v8
	v_lshl_add_u32 v12, v7, 2, v12
	v_add_u32_e32 v12, s38, v12
	v_readlane_b32 s44, v253, 57
	v_readlane_b32 s45, v253, 58
	s_lshl_b32 s39, s3, 6
	s_add_i32 s39, s39, s10
	s_lshl_b32 s39, s39, 2
	s_add_u32 s44, s44, s39
	s_addc_u32 s45, s45, 0
	v_lshlrev_b32_e32 v13, 4, v8
	global_load_dwordx4 v[156:159], v13, s[44:45]
	global_load_dwordx4 v[160:163], v13, s[44:45] offset:32
	global_load_dwordx4 v[164:167], v13, s[44:45] offset:64
	global_load_dwordx4 v[168:171], v13, s[44:45] offset:96
	global_load_dwordx4 v[172:175], v13, s[44:45] offset:128
	global_load_dwordx4 v[176:179], v13, s[44:45] offset:160
	global_load_dwordx4 v[180:183], v13, s[44:45] offset:192
	global_load_dwordx4 v[184:187], v13, s[44:45] offset:224
	s_waitcnt lgkmcnt(0)
; DI void pool_item(const Params& P, unsigned char* lds, const int l, const int tt, const int tid) {
;     ...
;         for (int c4 = 0; c4 < 16; ++c4) {
;           float w0 = pw[(c4 * 4 + 0) * 64], w1 = pw[(c4 * 4 + 1) * 64], w2 = pw[(c4 * 4 + 2) * 64], w3 = pw[(c4 * 4 + 3) * 64];
; #pragma unroll
;           for (int tk = 0; tk < 32; ++tk) {
;             float4 yv = *(const float4*)(Y + (tg * 32 + tk) * 256 + g * 64 + c4 * 4);
;             acc[tk] += yv.x * w0 + yv.y * w1 + yv.z * w2 + yv.w * w3;
;           }
;         }
	ds_read_b32 v124, v12
	ds_read_b32 v125, v12 offset:288
	ds_read_b32 v126, v12 offset:576
	ds_read_b32 v127, v12 offset:864
	ds_read_b32 v128, v12 offset:1152
	ds_read_b32 v129, v12 offset:1440
	ds_read_b32 v130, v12 offset:1728
	ds_read_b32 v131, v12 offset:2016
	ds_read_b32 v132, v12 offset:2304
	ds_read_b32 v133, v12 offset:2592
	ds_read_b32 v134, v12 offset:2880
	ds_read_b32 v135, v12 offset:3168
	ds_read_b32 v136, v12 offset:3456
	ds_read_b32 v137, v12 offset:3744
	ds_read_b32 v138, v12 offset:4032
	ds_read_b32 v139, v12 offset:4320
	ds_read_b32 v140, v12 offset:4608
	ds_read_b32 v141, v12 offset:4896
	ds_read_b32 v142, v12 offset:5184
	ds_read_b32 v143, v12 offset:5472
	ds_read_b32 v144, v12 offset:5760
	ds_read_b32 v145, v12 offset:6048
	ds_read_b32 v146, v12 offset:6336
	ds_read_b32 v147, v12 offset:6624
	ds_read_b32 v148, v12 offset:6912
	ds_read_b32 v149, v12 offset:7200
	ds_read_b32 v150, v12 offset:7488
	ds_read_b32 v151, v12 offset:7776
	ds_read_b32 v152, v12 offset:8064
	ds_read_b32 v153, v12 offset:8352
	ds_read_b32 v154, v12 offset:8640
	ds_read_b32 v155, v12 offset:8928
	s_lshl_b32 s39, s4, 5
	s_add_i32 s39, s39, s14
	v_add_u32_e32 v14, s39, v7
	v_lshlrev_b32_e32 v14, 11, v14
	s_lshl_b32 s39, s3, 7
	v_lshl_add_u32 v15, v8, 3, s39
	v_add_u32_e32 v14, v14, v15
	s_waitcnt vmcnt(8)
	s_waitcnt lgkmcnt(0)
	v_mfma_f32_32x32x2_f32 v[16:31], v60, v124, 0
	v_mfma_f32_32x32x2_f32 v[32:47], v61, v124, 0
	v_mfma_f32_32x32x2_f32 v[16:31], v62, v125, v[16:31]
	v_mfma_f32_32x32x2_f32 v[32:47], v63, v125, v[32:47]
	v_mfma_f32_32x32x2_f32 v[16:31], v64, v126, v[16:31]
	v_mfma_f32_32x32x2_f32 v[32:47], v65, v126, v[32:47]
	v_mfma_f32_32x32x2_f32 v[16:31], v66, v127, v[16:31]
	v_mfma_f32_32x32x2_f32 v[32:47], v67, v127, v[32:47]
	v_mfma_f32_32x32x2_f32 v[16:31], v68, v128, v[16:31]
	v_mfma_f32_32x32x2_f32 v[32:47], v69, v128, v[32:47]
	v_mfma_f32_32x32x2_f32 v[16:31], v70, v129, v[16:31]
	v_mfma_f32_32x32x2_f32 v[32:47], v71, v129, v[32:47]
	v_mfma_f32_32x32x2_f32 v[16:31], v72, v130, v[16:31]
	v_mfma_f32_32x32x2_f32 v[32:47], v73, v130, v[32:47]
	v_mfma_f32_32x32x2_f32 v[16:31], v74, v131, v[16:31]
	v_mfma_f32_32x32x2_f32 v[32:47], v75, v131, v[32:47]
	v_mfma_f32_32x32x2_f32 v[16:31], v76, v132, v[16:31]
	v_mfma_f32_32x32x2_f32 v[32:47], v77, v132, v[32:47]
	v_mfma_f32_32x32x2_f32 v[16:31], v78, v133, v[16:31]
	v_mfma_f32_32x32x2_f32 v[32:47], v79, v133, v[32:47]
	v_mfma_f32_32x32x2_f32 v[16:31], v80, v134, v[16:31]
	v_mfma_f32_32x32x2_f32 v[32:47], v81, v134, v[32:47]
	v_mfma_f32_32x32x2_f32 v[16:31], v82, v135, v[16:31]
	v_mfma_f32_32x32x2_f32 v[32:47], v83, v135, v[32:47]
	v_mfma_f32_32x32x2_f32 v[16:31], v84, v136, v[16:31]
	v_mfma_f32_32x32x2_f32 v[32:47], v85, v136, v[32:47]
	v_mfma_f32_32x32x2_f32 v[16:31], v86, v137, v[16:31]
	v_mfma_f32_32x32x2_f32 v[32:47], v87, v137, v[32:47]
	v_mfma_f32_32x32x2_f32 v[16:31], v88, v138, v[16:31]
	v_mfma_f32_32x32x2_f32 v[32:47], v89, v138, v[32:47]
	v_mfma_f32_32x32x2_f32 v[16:31], v90, v139, v[16:31]
	v_mfma_f32_32x32x2_f32 v[32:47], v91, v139, v[32:47]
	v_mfma_f32_32x32x2_f32 v[16:31], v92, v140, v[16:31]
	v_mfma_f32_32x32x2_f32 v[32:47], v93, v140, v[32:47]
	v_mfma_f32_32x32x2_f32 v[16:31], v94, v141, v[16:31]
	v_mfma_f32_32x32x2_f32 v[32:47], v95, v141, v[32:47]
	v_mfma_f32_32x32x2_f32 v[16:31], v96, v142, v[16:31]
	v_mfma_f32_32x32x2_f32 v[32:47], v97, v142, v[32:47]
	v_mfma_f32_32x32x2_f32 v[16:31], v98, v143, v[16:31]
	v_mfma_f32_32x32x2_f32 v[32:47], v99, v143, v[32:47]
	v_mfma_f32_32x32x2_f32 v[16:31], v100, v144, v[16:31]
	v_mfma_f32_32x32x2_f32 v[32:47], v101, v144, v[32:47]
	v_mfma_f32_32x32x2_f32 v[16:31], v102, v145, v[16:31]
	v_mfma_f32_32x32x2_f32 v[32:47], v103, v145, v[32:47]
	v_mfma_f32_32x32x2_f32 v[16:31], v104, v146, v[16:31]
	v_mfma_f32_32x32x2_f32 v[32:47], v105, v146, v[32:47]
	v_mfma_f32_32x32x2_f32 v[16:31], v106, v147, v[16:31]
	v_mfma_f32_32x32x2_f32 v[32:47], v107, v147, v[32:47]
	v_mfma_f32_32x32x2_f32 v[16:31], v108, v148, v[16:31]
	v_mfma_f32_32x32x2_f32 v[32:47], v109, v148, v[32:47]
	v_mfma_f32_32x32x2_f32 v[16:31], v110, v149, v[16:31]
	v_mfma_f32_32x32x2_f32 v[32:47], v111, v149, v[32:47]
	v_mfma_f32_32x32x2_f32 v[16:31], v112, v150, v[16:31]
	v_mfma_f32_32x32x2_f32 v[32:47], v113, v150, v[32:47]
	v_mfma_f32_32x32x2_f32 v[16:31], v114, v151, v[16:31]
	v_mfma_f32_32x32x2_f32 v[32:47], v115, v151, v[32:47]
	v_mfma_f32_32x32x2_f32 v[16:31], v116, v152, v[16:31]
	v_mfma_f32_32x32x2_f32 v[32:47], v117, v152, v[32:47]
	v_mfma_f32_32x32x2_f32 v[16:31], v118, v153, v[16:31]
	v_mfma_f32_32x32x2_f32 v[32:47], v119, v153, v[32:47]
	v_mfma_f32_32x32x2_f32 v[16:31], v120, v154, v[16:31]
	v_mfma_f32_32x32x2_f32 v[32:47], v121, v154, v[32:47]
	v_mfma_f32_32x32x2_f32 v[16:31], v122, v155, v[16:31]
	v_mfma_f32_32x32x2_f32 v[32:47], v123, v155, v[32:47]
	s_waitcnt vmcnt(0)
; DI u16 f2bf(float a) { return (u16)(pk2(a, 0.f) & 0xffffu); }
; DI void pool_item(const Params& P, unsigned char* lds, const int l, const int tt, const int tid) {
;     ...
;         const float psc = P.pool_scale[l * 256 + dcol];
; #pragma unroll
;         for (int tk = 0; tk < 32; ++tk)
;           mix[(size_t)(row0 + tg * 32 + tk) * DM + 256 + dcol] = f2bf(acc[tk] * psc);
;       }
;       __syncthreads();
	s_nop 15
	s_nop 7
	v_mul_f32_e32 v16, v156, v16
	v_mul_f32_e32 v17, v157, v17
	v_mul_f32_e32 v18, v158, v18
	v_mul_f32_e32 v19, v159, v19
	v_cvt_pk_bf16_f32 v48, v16, v17
	v_cvt_pk_bf16_f32 v49, v18, v19
	global_store_dwordx2 v14, v[48:49], s[0:1]
	v_mul_f32_e32 v20, v160, v20
	v_mul_f32_e32 v21, v161, v21
	v_mul_f32_e32 v22, v162, v22
	v_mul_f32_e32 v23, v163, v23
	v_cvt_pk_bf16_f32 v50, v20, v21
	v_cvt_pk_bf16_f32 v51, v22, v23
	global_store_dwordx2 v14, v[50:51], s[0:1] offset:16
	v_mul_f32_e32 v24, v164, v24
	v_mul_f32_e32 v25, v165, v25
	v_mul_f32_e32 v26, v166, v26
	v_mul_f32_e32 v27, v167, v27
	v_cvt_pk_bf16_f32 v52, v24, v25
	v_cvt_pk_bf16_f32 v53, v26, v27
	global_store_dwordx2 v14, v[52:53], s[0:1] offset:32
	v_mul_f32_e32 v28, v168, v28
	v_mul_f32_e32 v29, v169, v29
	v_mul_f32_e32 v30, v170, v30
	v_mul_f32_e32 v31, v171, v31
	v_cvt_pk_bf16_f32 v54, v28, v29
	v_cvt_pk_bf16_f32 v55, v30, v31
	global_store_dwordx2 v14, v[54:55], s[0:1] offset:48
	v_mul_f32_e32 v32, v172, v32
	v_mul_f32_e32 v33, v173, v33
	v_mul_f32_e32 v34, v174, v34
	v_mul_f32_e32 v35, v175, v35
	v_cvt_pk_bf16_f32 v48, v32, v33
	v_cvt_pk_bf16_f32 v49, v34, v35
	global_store_dwordx2 v14, v[48:49], s[0:1] offset:64
	v_mul_f32_e32 v36, v176, v36
	v_mul_f32_e32 v37, v177, v37
	v_mul_f32_e32 v38, v178, v38
	v_mul_f32_e32 v39, v179, v39
	v_cvt_pk_bf16_f32 v50, v36, v37
	v_cvt_pk_bf16_f32 v51, v38, v39
	global_store_dwordx2 v14, v[50:51], s[0:1] offset:80
	v_mul_f32_e32 v40, v180, v40
	v_mul_f32_e32 v41, v181, v41
	v_mul_f32_e32 v42, v182, v42
	v_mul_f32_e32 v43, v183, v43
	v_cvt_pk_bf16_f32 v52, v40, v41
	v_cvt_pk_bf16_f32 v53, v42, v43
	global_store_dwordx2 v14, v[52:53], s[0:1] offset:96
	v_mul_f32_e32 v44, v184, v44
	v_mul_f32_e32 v45, v185, v45
	v_mul_f32_e32 v46, v186, v46
	v_mul_f32_e32 v47, v187, v47
	v_cvt_pk_bf16_f32 v54, v44, v45
	v_cvt_pk_bf16_f32 v55, v46, v47
	global_store_dwordx2 v14, v[54:55], s[0:1] offset:112
	v_readlane_b32 s36, v253, 43
	v_readlane_b32 s37, v253, 44
	v_readlane_b32 s38, v253, 45
	v_readlane_b32 s39, v253, 46
	v_readlane_b32 s40, v253, 47
	v_readlane_b32 s41, v253, 48
	v_readlane_b32 s42, v253, 49
	v_readlane_b32 s43, v253, 50
	v_readlane_b32 s44, v253, 51
	v_readlane_b32 s45, v253, 52
	v_readlane_b32 s46, v253, 53
	v_readlane_b32 s47, v253, 54
	v_readlane_b32 s48, v253, 55
	v_readlane_b32 s49, v253, 56
	v_readlane_b32 s50, v253, 57
	v_readlane_b32 s51, v253, 58
	s_add_i32 s9, s9, s88
	s_sub_i32 s11, s11, s19
	s_add_i32 s12, s12, s19
	s_add_i32 s13, s13, s19
	s_cmp_ge_i32 s9, s8
	s_barrier
	s_cbranch_scc0 .LBB0_484
